# scan: GDN consumer vmcnt waits re-derived for steady state; scan loaders wait vmcnt(0) per trip (one chunk in flight)
# speedup vs baseline: 1.0015x; 1.0015x over previous
.LBB0_338:
	s_waitcnt vmcnt(0)
	ds_write_b128 v117, v[14:17]
	s_waitcnt vmcnt(23)
	ds_write_b128 v115, v[22:25] offset:18432
	v_add_u32_e32 v14, s33, v115
	v_add_u32_e32 v118, 0, v113
	s_waitcnt vmcnt(21)
	ds_write_b128 v14, v[18:21] offset:38912
	ds_write_b128 v117, v[2:5] offset:4608
	ds_write_b128 v115, v[10:13] offset:23552
	s_waitcnt vmcnt(20)
	ds_write_b128 v14, v[6:9] offset:44032
	s_waitcnt vmcnt(19)
	ds_write_b128 v117, v[26:29] offset:9216
	s_waitcnt vmcnt(17)
	ds_write_b128 v115, v[34:37] offset:28672
	ds_write_b128 v117, v[30:33] offset:13824
	s_waitcnt vmcnt(16)
	ds_write_b128 v115, v[42:45] offset:33792
	s_waitcnt vmcnt(15)
	ds_write_b128 v115, v[50:53] offset:59392
	s_waitcnt vmcnt(14)
	ds_write_b128 v115, v[46:49] offset:64512
	s_and_saveexec_b64 s[2:3], s[4:5]
	s_cbranch_execz .LBB0_340
	v_add_u32_e32 v2, 0x26000, v118
	s_waitcnt vmcnt(13)
	ds_write_b128 v2, v[38:41]

.LBB0_342:
	s_or_b64 exec, exec, s[2:3]
	s_waitcnt lgkmcnt(0)
	s_barrier
	v_add_u32_e32 v119, 0x13000, v117
	s_waitcnt vmcnt(0)
	ds_write_b128 v119, v[62:65]
	v_add_u32_e32 v62, 0x17800, v115
	s_waitcnt vmcnt(23)
	ds_write_b128 v62, v[70:73]
	s_waitcnt vmcnt(21)
	ds_write_b128 v116, v[74:77]
	ds_write_b128 v119, v[54:57] offset:4608
	ds_write_b128 v62, v[58:61] offset:5120
	s_waitcnt vmcnt(20)
	ds_write_b128 v116, v[66:69] offset:5120
	s_waitcnt vmcnt(19)
	ds_write_b128 v119, v[82:85] offset:9216
	s_waitcnt vmcnt(17)
	ds_write_b128 v62, v[90:93] offset:10240
	ds_write_b128 v119, v[86:89] offset:13824
	s_waitcnt vmcnt(16)
	ds_write_b128 v62, v[94:97] offset:15360
	v_add_u32_e32 v54, 0x21800, v115
	s_waitcnt vmcnt(15)
	ds_write_b128 v54, v[102:105]
	s_waitcnt vmcnt(14)
	ds_write_b128 v54, v[98:101] offset:5120
	s_and_saveexec_b64 s[2:3], s[4:5]
	s_cbranch_execz .LBB0_344
	v_add_u32_e32 v54, 0x26200, v118
	s_waitcnt vmcnt(13)
	ds_write_b128 v54, v[78:81]

.LBB0_348:
	s_andn2_b64 vcc, exec, s[2:3]
	s_cbranch_vccnz .LBB0_377
	s_lshl_b32 s4, s64, 2
	s_and_b32 s16, s4, 28
	s_ashr_i32 s2, s64, 4
	s_add_i32 s16, s16, s2
	s_ashr_i32 s12, s16, 3
	s_bfe_u32 s17, s64, 0x10003
	s_ashr_i32 s13, s12, 31
	s_mov_b32 s8, 2
	s_cmpk_lt_u32 s90, 0x100
	s_mov_b64 s[2:3], -1
	s_cbranch_scc0 .LBB0_353
	s_lshl_b32 s2, s91, 4
	s_lshl_b32 s3, s17, 6
	s_or_b32 s10, s2, s3
	s_lshr_b32 s5, s64, 4
	s_setprio 3
	s_lshl_b32 s2, s16, 6
	s_ashr_i32 s3, s2, 31
	s_lshl_b64 s[6:7], s[2:3], 7
	s_or_b32 s3, s6, s10
	s_or_b32 s6, s2, 1
	s_waitcnt vmcnt(24)
	v_mov_b32_e32 v3, s7
	s_ashr_i32 s7, s6, 31
	s_lshl_b64 s[6:7], s[6:7], 7
	v_or_b32_e32 v2, s3, v1
	s_or_b32 s3, s6, s10
	v_readlane_b32 s36, v253, 41
	s_waitcnt vmcnt(22)
	v_or_b32_e32 v10, s3, v1
	v_mov_b32_e32 v11, s7
	v_lshlrev_b64 v[2:3], 7, v[2:3]
	v_readlane_b32 s48, v253, 53
	v_readlane_b32 s49, v253, 54
	v_lshlrev_b64 v[10:11], 7, v[10:11]
	s_waitcnt vmcnt(21)
	v_lshlrev_b32_e32 v18, 4, v111
	v_lshl_add_u64 v[2:3], s[48:49], 0, v[2:3]
	v_mov_b32_e32 v19, 0
	v_lshl_add_u64 v[10:11], s[48:49], 0, v[10:11]
	v_lshl_add_u64 v[2:3], v[2:3], 0, v[18:19]
	v_lshl_add_u64 v[10:11], v[10:11], 0, v[18:19]
	global_load_dwordx4 v[6:9], v[2:3], off
	s_nop 0
	global_load_dwordx4 v[2:5], v[2:3], off offset:64
	s_nop 0
	global_load_dwordx4 v[14:17], v[10:11], off
	s_nop 0
	global_load_dwordx4 v[10:13], v[10:11], off offset:64
	s_add_i32 s6, 0, 0x9000
	v_add_u32_e32 v179, s6, v110
	s_add_i32 s6, 0, 0x13000
	s_add_i32 s4, s4, s5
	v_add_u32_e32 v181, s6, v109
	s_add_i32 s6, 0, 0x1c000
	s_and_b32 s4, s4, 7
	v_add_u32_e32 v182, s6, v110
	s_lshl_b64 s[6:7], s[12:13], 23
	s_lshl_b32 s4, s4, 8
	s_add_i32 s14, 0, 0x26000
	s_add_i32 s22, 0, 0x26400
	s_or_b32 s9, s2, 3
	s_or_b32 s4, s6, s4
	s_lshl_b32 s5, s10, 1
	s_add_u32 s4, s4, s5
	v_readlane_b32 s50, v253, 55
	s_addc_u32 s5, s7, 0
	v_readlane_b32 s51, v253, 56
	s_add_u32 s4, s50, s4
	s_waitcnt lgkmcnt(0)
	s_barrier
	s_addc_u32 s5, s51, s5
	v_lshl_add_u64 v[172:173], s[48:49], 0, v[18:19]
	v_or_b32_e32 v18, s10, v1
	s_add_u32 s10, s4, 0x13020000
	v_add_u32_e32 v178, 0, v109
	s_mov_b32 s3, 0x9000
	v_add_u32_e32 v180, s14, v108
	v_add_u32_e32 v183, s22, v108
	s_addc_u32 s11, s5, 0
	v_lshlrev_b64 v[174:175], 7, v[18:19]
	v_mov_b32_e32 v184, s14
	s_mov_b32 s6, 0x20000
	s_movk_i32 s14, 0x1000
	s_mov_b32 s15, 0x8000
	s_mov_b32 s18, 0x10000
	s_mov_b32 s19, 0x11000
	s_mov_b32 s20, 0x18000
	s_mov_b32 s21, 0x19000
	v_mov_b32_e32 v185, s22
	v_mov_b32_e32 v18, v19
	v_mov_b32_e32 v20, v19
	v_mov_b32_e32 v21, v19
	s_waitcnt vmcnt(18)
	v_mov_b32_e32 v46, v19
	v_mov_b32_e32 v47, v19
	v_mov_b32_e32 v48, v19
	v_mov_b32_e32 v49, v19
	v_mov_b32_e32 v42, v19
	v_mov_b32_e32 v43, v19
	v_mov_b32_e32 v44, v19
	v_mov_b32_e32 v45, v19
	s_waitcnt vmcnt(17)
	v_mov_b32_e32 v38, v19
	v_mov_b32_e32 v39, v19
	v_mov_b32_e32 v40, v19
	v_mov_b32_e32 v41, v19
	v_mov_b32_e32 v34, v19
	v_mov_b32_e32 v35, v19
	v_mov_b32_e32 v36, v19
	v_mov_b32_e32 v37, v19
	v_mov_b32_e32 v30, v19
	v_mov_b32_e32 v31, v19
	v_mov_b32_e32 v32, v19
	v_mov_b32_e32 v33, v19
	v_mov_b32_e32 v26, v19
	v_mov_b32_e32 v27, v19
	v_mov_b32_e32 v28, v19
	v_mov_b32_e32 v29, v19
	v_mov_b32_e32 v22, v19
	v_mov_b32_e32 v23, v19
	v_mov_b32_e32 v24, v19
	v_mov_b32_e32 v25, v19
	v_readlane_b32 s37, v253, 42
	v_readlane_b32 s38, v253, 43
	v_readlane_b32 s39, v253, 44
	v_readlane_b32 s40, v253, 45
	v_readlane_b32 s41, v253, 46
	v_readlane_b32 s42, v253, 47
	v_readlane_b32 s43, v253, 48
	v_readlane_b32 s44, v253, 49
	v_readlane_b32 s45, v253, 50
	v_readlane_b32 s46, v253, 51
	v_readlane_b32 s47, v253, 52
	s_waitcnt vmcnt(0)
.LBB0_351:
	ds_read_b128 v[50:53], v179 offset:0x5000
	s_add_i32 s22, s8, -2
	ds_read_b128 v[54:57], v179 offset:0x5a00
	ds_read_b128 v[58:61], v179 offset:0x6400
	ds_read_b128 v[62:65], v179 offset:0x6e00
	ds_read_b128 v[66:69], v179 offset:0x6440
	ds_read_b128 v[106:109], v179 offset:0x6e40
	ds_read_b128 v[102:105], v178 offset:0
	ds_read_b128 v[98:101], v178 offset:0x1200
	ds_read_b128 v[94:97], v178 offset:0x2400
	ds_read_b128 v[90:93], v178 offset:0x3600
	ds_read_b128 v[86:89], v178 offset:64
	s_waitcnt lgkmcnt(10)
	ds_read_b128 v[82:85], v178 offset:0x1240
	s_waitcnt lgkmcnt(10)
	ds_read_b128 v[78:81], v178 offset:0x2440
	s_waitcnt lgkmcnt(10)
	s_cmp_lt_u32 s22, 62
	s_waitcnt vmcnt(19)
	v_mfma_f32_16x16x32_bf16 v[118:121], v[50:53], v[6:9], 0
	ds_read_b128 v[74:77], v178 offset:0x3640
	s_waitcnt lgkmcnt(10)
	s_cselect_b32 s4, s8, 63
	v_mfma_f32_16x16x32_bf16 v[50:53], v[58:61], v[6:9], 0
	s_add_i32 s4, s4, s2
	ds_read_b128 v[70:73], v178 offset:0x80
	s_waitcnt lgkmcnt(10)
	v_mfma_f32_16x16x32_bf16 v[110:113], v[54:57], v[6:9], 0
	s_ashr_i32 s5, s4, 31
	s_lshl_b64 s[4:5], s[4:5], 14
	v_cvt_pk_bf16_f32 v54, v30, v31
	v_mfma_f32_16x16x32_bf16 v[6:9], v[62:65], v[6:9], 0
	v_cvt_pk_bf16_f32 v55, v32, v33
	v_cvt_pk_bf16_f32 v56, v34, v35
	v_cvt_pk_bf16_f32 v57, v36, v37
	s_waitcnt vmcnt(18)
	v_mfma_f32_16x16x32_bf16 v[114:117], v[66:69], v[2:5], v[50:53]
	ds_read_b128 v[66:69], v178 offset:0x1280
	s_waitcnt lgkmcnt(10)
	v_cvt_pk_bf16_f32 v58, v38, v39
	v_mfma_f32_16x16x32_bf16 v[106:109], v[106:109], v[2:5], v[6:9]
	v_or_b32_e32 v3, s5, v175
	v_or_b32_e32 v2, s4, v174
	v_lshl_add_u64 v[2:3], v[172:173], 0, v[2:3]
	global_load_dwordx4 v[6:9], v[2:3], off
	s_nop 0
	global_load_dwordx4 v[2:5], v[2:3], off offset:64
	v_cvt_pk_bf16_f32 v50, v22, v23
	v_cvt_pk_bf16_f32 v51, v24, v25
	v_cvt_pk_bf16_f32 v52, v26, v27
	v_cvt_pk_bf16_f32 v53, v28, v29
	ds_read_b128 v[126:129], v178 offset:0x2480
	s_waitcnt lgkmcnt(10)
	v_cvt_pk_bf16_f32 v59, v40, v41
	v_cvt_pk_bf16_f32 v60, v42, v43
	v_mfma_f32_16x16x32_bf16 v[102:105], v[102:105], v[50:53], v[118:121]
	ds_read_b128 v[118:121], v178 offset:0x3680
	s_waitcnt lgkmcnt(10)
	v_cvt_pk_bf16_f32 v61, v44, v45
	v_mfma_f32_16x16x32_bf16 v[98:101], v[98:101], v[50:53], v[110:113]
	ds_read_b128 v[110:113], v178 offset:0xc0
	s_waitcnt lgkmcnt(10)
	ds_read_b128 v[134:137], v178 offset:0x12c0
	s_waitcnt lgkmcnt(10)
	v_cvt_pk_bf16_f32 v62, v46, v47
	v_mfma_f32_16x16x32_bf16 v[94:97], v[94:97], v[50:53], v[114:117]
	v_cvt_pk_bf16_f32 v63, v48, v49
	v_cvt_pk_bf16_f32 v64, v18, v19
	v_cvt_pk_bf16_f32 v65, v20, v21
	v_mfma_f32_16x16x32_bf16 v[90:93], v[90:93], v[50:53], v[106:109]
	ds_read_b128 v[106:109], v178 offset:0x24c0
	s_waitcnt lgkmcnt(10)
	s_add_u32 s4, s10, 0xfffe0000
	v_mfma_f32_16x16x32_bf16 v[86:89], v[86:89], v[54:57], v[102:105]
	ds_read_b128 v[102:105], v178 offset:0x36c0
	s_waitcnt lgkmcnt(10)
	ds_read_b128 v[154:157], v178 offset:0x4800
	s_waitcnt lgkmcnt(10)
	ds_read_b128 v[150:153], v178 offset:0x5a00
	s_waitcnt lgkmcnt(10)
	s_addc_u32 s5, s11, -1
	v_mfma_f32_16x16x32_bf16 v[82:85], v[82:85], v[54:57], v[98:101]
	s_and_b32 s5, s5, 0xffff
	s_mov_b32 s7, s6
	s_add_i32 s8, s8, 2
	v_mfma_f32_16x16x32_bf16 v[78:81], v[78:81], v[54:57], v[94:97]
	ds_read_b128 v[94:97], v178 offset:0x4840
	s_waitcnt lgkmcnt(10)
	ds_read_b128 v[114:117], v178 offset:0x5a40
	v_mfma_f32_16x16x32_bf16 v[74:77], v[74:77], v[54:57], v[90:93]
	s_waitcnt lgkmcnt(10)
	ds_read_b128 v[122:125], v178 offset:0x4880
	s_waitcnt lgkmcnt(10)
	v_mfma_f32_16x16x32_bf16 v[70:73], v[70:73], v[58:61], v[86:89]
	ds_read_b128 v[130:133], v178 offset:0x5a80
	s_waitcnt lgkmcnt(10)
	ds_read_b128 v[138:141], v178 offset:0x48c0
	v_mfma_f32_16x16x32_bf16 v[66:69], v[66:69], v[58:61], v[82:85]
	s_waitcnt lgkmcnt(10)
	ds_read_b128 v[142:145], v178 offset:0x5ac0
	s_waitcnt lgkmcnt(10)
	v_mfma_f32_16x16x32_bf16 v[78:81], v[126:129], v[58:61], v[78:81]
	ds_read_b128 v[162:165], v180 offset:0x200
	s_waitcnt lgkmcnt(10)
	ds_read_b128 v[166:169], v180 offset:0x240
	v_mfma_f32_16x16x32_bf16 v[74:77], v[118:121], v[58:61], v[74:77]
	s_waitcnt lgkmcnt(10)
	ds_read_b128 v[186:189], v180 offset:0x280
	s_waitcnt lgkmcnt(10)
	v_mfma_f32_16x16x32_bf16 v[146:149], v[110:113], v[62:65], v[70:73]
	ds_read_b128 v[190:193], v180 offset:0x2c0
	s_waitcnt lgkmcnt(10)
	ds_read_b32 v194, v184 offset:0x1fc
	v_mfma_f32_16x16x32_bf16 v[158:161], v[134:137], v[62:65], v[66:69]
	s_waitcnt lgkmcnt(10)
	ds_read_b128 v[134:137], v179 offset:0
	s_waitcnt lgkmcnt(10)
	v_mfma_f32_16x16x32_bf16 v[106:109], v[106:109], v[62:65], v[78:81]
	ds_read_b128 v[126:129], v179 offset:0xa00
	s_waitcnt lgkmcnt(10)
	ds_read_b128 v[118:121], v179 offset:0x1400
	v_mfma_f32_16x16x32_bf16 v[74:77], v[102:105], v[62:65], v[74:77]
	s_waitcnt lgkmcnt(10)
	ds_read_b128 v[110:113], v179 offset:0x1e00
	s_waitcnt lgkmcnt(10)
	ds_read_b128 v[98:101], v179 offset:0x2800
	s_waitcnt lgkmcnt(10)
	s_nop 4
	v_cvt_pk_bf16_f32 v70, v146, v147
	v_cvt_pk_bf16_f32 v71, v148, v149
	ds_read_b128 v[102:105], v179 offset:0x3200
	s_waitcnt lgkmcnt(10)
	v_cvt_pk_bf16_f32 v72, v158, v159
	v_pk_mul_f32 v[148:149], v[148:149], v[164:165]
	v_pk_mul_f32 v[146:147], v[146:147], v[162:163]
	v_cvt_pk_bf16_f32 v73, v160, v161
	v_cvt_pk_bf16_f32 v66, v106, v107
	ds_read_b128 v[90:93], v179 offset:0x3c00
	s_waitcnt lgkmcnt(10)
	ds_read_b128 v[86:89], v179 offset:0x4600
	s_waitcnt lgkmcnt(10)
	ds_read_b128 v[82:85], v179 offset:64
	s_waitcnt lgkmcnt(10)
	ds_read_b128 v[78:81], v179 offset:0xa40
	s_waitcnt lgkmcnt(10)
	s_nop 0
	v_pk_mul_f32 v[160:161], v[160:161], v[168:169]
	v_pk_mul_f32 v[158:159], v[158:159], v[166:167]
	v_pk_mul_f32 v[164:165], v[106:107], v[186:187]
	v_cvt_pk_bf16_f32 v106, v146, v147
	v_cvt_pk_bf16_f32 v107, v148, v149
	v_pk_mul_f32 v[148:149], v[194:195], v[32:33] op_sel_hi:[0,1]
	v_pk_mul_f32 v[146:147], v[194:195], v[30:31] op_sel_hi:[0,1]
	v_pk_mul_f32 v[32:33], v[194:195], v[40:41] op_sel_hi:[0,1]
	v_pk_mul_f32 v[30:31], v[194:195], v[38:39] op_sel_hi:[0,1]
	v_mfma_f32_16x16x32_bf16 v[38:41], v[154:157], v[50:53], 0
	v_cvt_pk_bf16_f32 v67, v108, v109
	v_pk_mul_f32 v[162:163], v[108:109], v[188:189]
	v_cvt_pk_bf16_f32 v108, v158, v159
	v_cvt_pk_bf16_f32 v109, v160, v161
	v_pk_mul_f32 v[160:161], v[194:195], v[28:29] op_sel_hi:[0,1]
	v_pk_mul_f32 v[158:159], v[194:195], v[26:27] op_sel_hi:[0,1]
	v_pk_mul_f32 v[28:29], v[194:195], v[44:45] op_sel_hi:[0,1]
	v_pk_mul_f32 v[26:27], v[194:195], v[42:43] op_sel_hi:[0,1]
	v_mfma_f32_16x16x32_bf16 v[42:45], v[150:153], v[50:53], 0
	v_cvt_pk_bf16_f32 v68, v74, v75
	v_cvt_pk_bf16_f32 v69, v76, v77
	v_pk_mul_f32 v[166:167], v[76:77], v[192:193]
	v_mfma_f32_16x16x32_bf16 v[38:41], v[94:97], v[54:57], v[38:41]
	v_mul_f32_e64 v76, v74, v190
	v_mul_f32_e64 v77, v75, v191
	v_cvt_pk_bf16_f32 v74, v164, v165
	v_cvt_pk_bf16_f32 v75, v162, v163
	v_mfma_f32_16x16x32_bf16 v[42:45], v[114:117], v[54:57], v[42:45]
	v_mul_f32_e64 v164, v194, v24
	v_mul_f32_e64 v165, v194, v25
	v_pk_mul_f32 v[162:163], v[194:195], v[22:23] op_sel_hi:[0,1]
	v_pk_mul_f32 v[24:25], v[194:195], v[48:49] op_sel_hi:[0,1]
	v_mfma_f32_16x16x32_bf16 v[38:41], v[122:125], v[58:61], v[38:41]
	v_mul_f32_e64 v22, v194, v46
	v_mul_f32_e64 v23, v194, v47
	v_pk_mul_f32 v[36:37], v[194:195], v[36:37] op_sel_hi:[0,1]
	v_pk_mul_f32 v[34:35], v[194:195], v[34:35] op_sel_hi:[0,1]
	v_mfma_f32_16x16x32_bf16 v[42:45], v[130:133], v[58:61], v[42:45]
	v_mul_f32_e64 v20, v194, v20
	v_mul_f32_e64 v21, v194, v21
	v_pk_mul_f32 v[18:19], v[194:195], v[18:19] op_sel_hi:[0,1]
	v_cvt_pk_bf16_f32 v76, v76, v77
	v_mfma_f32_16x16x32_bf16 v[94:97], v[138:141], v[62:65], v[38:41]
	ds_read_b128 v[38:41], v179 offset:0x1440
	s_waitcnt lgkmcnt(10)
	ds_read_b128 v[46:49], v179 offset:0x1e40
	s_waitcnt lgkmcnt(10)
	v_mfma_f32_16x16x32_bf16 v[114:117], v[142:145], v[62:65], v[42:45]
	v_cvt_pk_bf16_f32 v77, v166, v167
	v_mfma_f32_16x16x32_bf16 v[42:45], v[134:137], v[106:109], v[162:165]
	v_mfma_f32_16x16x32_bf16 v[122:125], v[126:129], v[106:109], v[158:161]
	ds_read_b128 v[126:129], v179 offset:0x2840
	s_waitcnt lgkmcnt(10)
	ds_read_b128 v[130:133], v179 offset:0x3240
	s_waitcnt lgkmcnt(10)
	s_nop 0
	v_mfma_f32_16x16x32_bf16 v[34:37], v[110:113], v[106:109], v[34:37]
	ds_read_b128 v[110:113], v179 offset:0x3c40
	s_waitcnt lgkmcnt(10)
	ds_read_b128 v[134:137], v179 offset:0x4640
	s_waitcnt lgkmcnt(10)
	v_mfma_f32_16x16x32_bf16 v[118:121], v[118:121], v[106:109], v[146:149]
	ds_read_b128 v[138:141], v179 offset:0x7800
	s_waitcnt lgkmcnt(10)
	ds_read_b128 v[142:145], v179 offset:0x8200
	v_mfma_f32_16x16x32_bf16 v[98:101], v[98:101], v[106:109], v[30:33]
	s_waitcnt lgkmcnt(10)
	v_mfma_f32_16x16x32_bf16 v[102:105], v[102:105], v[106:109], v[26:29]
	v_mfma_f32_16x16x32_bf16 v[90:93], v[90:93], v[106:109], v[22:25]
	v_mfma_f32_16x16x32_bf16 v[86:89], v[86:89], v[106:109], v[18:21]
	ds_read_b128 v[106:109], v179 offset:0x8c00
	s_waitcnt lgkmcnt(10)
	s_nop 0
	v_mfma_f32_16x16x32_bf16 v[18:21], v[82:85], v[74:77], v[42:45]
	ds_read_b128 v[82:85], v179 offset:0x9600
	s_waitcnt lgkmcnt(10)
	s_nop 0
	v_mfma_f32_16x16x32_bf16 v[22:25], v[78:81], v[74:77], v[122:125]
	ds_read_b128 v[78:81], v179 offset:0x8c40
	s_waitcnt lgkmcnt(10)
	s_nop 0
	v_mfma_f32_16x16x32_bf16 v[26:29], v[38:41], v[74:77], v[118:121]
	ds_read_b128 v[118:121], v179 offset:0x9640
	s_waitcnt lgkmcnt(10)
	ds_read_b128 v[122:125], v178 offset:0x6c00
	s_waitcnt lgkmcnt(10)
	s_nop 0
	v_mfma_f32_16x16x32_bf16 v[30:33], v[46:49], v[74:77], v[34:37]
	v_mfma_f32_16x16x32_bf16 v[34:37], v[126:129], v[74:77], v[98:101]
	ds_read_b128 v[98:101], v178 offset:0x7e00
	s_waitcnt lgkmcnt(10)
	s_nop 0
	v_mfma_f32_16x16x32_bf16 v[38:41], v[130:133], v[74:77], v[102:105]
	ds_read_b128 v[102:105], v178 offset:0x6c40
	s_waitcnt lgkmcnt(10)
	s_nop 0
	v_mfma_f32_16x16x32_bf16 v[42:45], v[110:113], v[74:77], v[90:93]
	ds_read_b128 v[90:93], v178 offset:0x7e40
	s_waitcnt lgkmcnt(10)
	s_nop 0
	v_mfma_f32_16x16x32_bf16 v[46:49], v[134:137], v[74:77], v[86:89]
	ds_read_b128 v[74:77], v178 offset:0x6c80
	s_waitcnt lgkmcnt(10)
	ds_read_b128 v[110:113], v178 offset:0x7e80
	s_waitcnt lgkmcnt(10)
	ds_read_b128 v[130:133], v178 offset:0x6cc0
	s_waitcnt lgkmcnt(10)
	ds_read_b128 v[134:137], v178 offset:0x7ec0
	s_nop 0
	v_mfma_f32_16x16x32_bf16 v[86:89], v[138:141], v[70:73], 0
	s_waitcnt lgkmcnt(10)
	v_mfma_f32_16x16x32_bf16 v[106:109], v[106:109], v[70:73], 0
	v_mfma_f32_16x16x32_bf16 v[126:129], v[142:145], v[70:73], 0
	v_mfma_f32_16x16x32_bf16 v[70:73], v[82:85], v[70:73], 0
	ds_read_b128 v[82:85], v180 offset:0x100
	s_waitcnt lgkmcnt(10)
	s_nop 0
	v_mfma_f32_16x16x32_bf16 v[78:81], v[78:81], v[66:69], v[106:109]
	ds_read_b128 v[106:109], v180 offset:0x140
	s_waitcnt lgkmcnt(10)
	s_nop 0
	v_mfma_f32_16x16x32_bf16 v[66:69], v[118:121], v[66:69], v[70:73]
	ds_read_b128 v[70:73], v180 offset:0x180
	s_waitcnt lgkmcnt(10)
	s_nop 0
	v_mfma_f32_16x16x32_bf16 v[118:121], v[122:125], v[50:53], 0
	ds_read_b128 v[122:125], v180 offset:0x1c0
	s_waitcnt lgkmcnt(10)
	s_waitcnt lgkmcnt(9)
	s_waitcnt lgkmcnt(8)
	s_waitcnt lgkmcnt(7)
	s_waitcnt lgkmcnt(6)
	s_waitcnt lgkmcnt(5)
	s_nop 0
	v_mfma_f32_16x16x32_bf16 v[50:53], v[98:101], v[50:53], 0
	s_waitcnt lgkmcnt(4)
	s_waitcnt lgkmcnt(3)
	s_waitcnt lgkmcnt(2)
	v_mfma_f32_16x16x32_bf16 v[98:101], v[102:105], v[54:57], v[118:121]
	s_waitcnt lgkmcnt(1)
	s_waitcnt lgkmcnt(0)
	v_mfma_f32_16x16x32_bf16 v[50:53], v[90:93], v[54:57], v[50:53]
	v_mfma_f32_16x16x32_bf16 v[54:57], v[74:77], v[58:61], v[98:101]
	v_fma_f32 v74, v94, v82, v86
	v_fma_f32 v75, v95, v83, v87
	v_pk_fma_f32 v[82:83], v[114:115], v[106:107], v[126:127]
	v_pk_fma_f32 v[76:77], v[116:117], v[108:109], v[128:129]
	v_mfma_f32_16x16x32_bf16 v[50:53], v[110:113], v[58:61], v[50:53]
	v_mfma_f32_16x16x32_bf16 v[56:59], v[130:133], v[62:65], v[54:57]
	v_mfma_f32_16x16x32_bf16 v[60:63], v[134:137], v[62:65], v[50:53]
	v_fma_f32 v64, v96, v84, v88
	v_fma_f32 v65, v97, v85, v89
	s_nop 4
	v_pk_fma_f32 v[54:55], v[58:59], v[72:73], v[80:81]
	v_cvt_pk_bf16_f32 v58, v74, v75
	v_pk_fma_f32 v[56:57], v[56:57], v[70:71], v[78:79]
	v_cvt_pk_bf16_f32 v54, v54, v55
	v_mov_b32_dpp v59, v58 quad_perm:[1,0,3,2] row_mask:0xf bank_mask:0xf bound_ctrl:1
	v_perm_b32 v58, v59, v58, v176
	buffer_store_dword v58, v177, s[4:7], 0 offen
	v_cvt_pk_bf16_f32 v58, v64, v65
	v_pk_fma_f32 v[50:51], v[62:63], v[124:125], v[68:69]
	v_pk_fma_f32 v[52:53], v[60:61], v[122:123], v[66:67]
	v_mov_b32_dpp v59, v58 quad_perm:[1,0,3,2] row_mask:0xf bank_mask:0xf bound_ctrl:1
	v_perm_b32 v58, v59, v58, v176
	buffer_store_dword v58, v177, s[4:7], s14 offen
	v_cvt_pk_bf16_f32 v58, v82, v83
	v_cvt_pk_bf16_f32 v56, v56, v57
	v_cvt_pk_bf16_f32 v52, v52, v53
	v_mov_b32_dpp v59, v58 quad_perm:[1,0,3,2] row_mask:0xf bank_mask:0xf bound_ctrl:1
	v_perm_b32 v58, v59, v58, v176
	buffer_store_dword v58, v177, s[4:7], s15 offen
	v_cvt_pk_bf16_f32 v58, v76, v77
	v_cvt_pk_bf16_f32 v50, v50, v51
	v_mov_b32_dpp v57, v56 quad_perm:[1,0,3,2] row_mask:0xf bank_mask:0xf bound_ctrl:1
	v_mov_b32_dpp v59, v58 quad_perm:[1,0,3,2] row_mask:0xf bank_mask:0xf bound_ctrl:1
	v_mov_b32_dpp v55, v54 quad_perm:[1,0,3,2] row_mask:0xf bank_mask:0xf bound_ctrl:1
	v_mov_b32_dpp v53, v52 quad_perm:[1,0,3,2] row_mask:0xf bank_mask:0xf bound_ctrl:1
	v_mov_b32_dpp v51, v50 quad_perm:[1,0,3,2] row_mask:0xf bank_mask:0xf bound_ctrl:1
	v_perm_b32 v58, v59, v58, v176
	v_perm_b32 v56, v57, v56, v176
	v_perm_b32 v54, v55, v54, v176
	v_perm_b32 v52, v53, v52, v176
	v_perm_b32 v50, v51, v50, v176
	buffer_store_dword v58, v177, s[4:7], s3 offen
	buffer_store_dword v56, v177, s[4:7], s18 offen
	buffer_store_dword v54, v177, s[4:7], s19 offen
	buffer_store_dword v52, v177, s[4:7], s20 offen
	buffer_store_dword v50, v177, s[4:7], s21 offen
	s_waitcnt lgkmcnt(0)
	s_barrier
	ds_read_b128 v[50:53], v182 offset:0x5000
	ds_read_b128 v[54:57], v182 offset:0x5a00
	ds_read_b128 v[58:61], v182 offset:0x6400
	ds_read_b128 v[62:65], v182 offset:0x6e00
	ds_read_b128 v[66:69], v182 offset:0x6440
	ds_read_b128 v[106:109], v182 offset:0x6e40
	ds_read_b128 v[102:105], v181 offset:0
	ds_read_b128 v[98:101], v181 offset:0x1200
	ds_read_b128 v[94:97], v181 offset:0x2400
	ds_read_b128 v[90:93], v181 offset:0x3600
	ds_read_b128 v[86:89], v181 offset:64
	s_nop 0
	s_waitcnt lgkmcnt(10)
	ds_read_b128 v[82:85], v181 offset:0x1240
	s_waitcnt lgkmcnt(10)
	ds_read_b128 v[78:81], v181 offset:0x2440
	s_waitcnt lgkmcnt(10)
	ds_read_b128 v[74:77], v181 offset:0x3640
	s_waitcnt vmcnt(19)
	v_mfma_f32_16x16x32_bf16 v[118:121], v[50:53], v[14:17], 0
	s_waitcnt lgkmcnt(10)
	s_min_u32 s4, s22, 60
	s_add_i32 s4, s9, s4
	v_mfma_f32_16x16x32_bf16 v[50:53], v[58:61], v[14:17], 0
	ds_read_b128 v[70:73], v181 offset:0x80
	s_waitcnt lgkmcnt(10)
	s_ashr_i32 s5, s4, 31
	v_mfma_f32_16x16x32_bf16 v[110:113], v[54:57], v[14:17], 0
	s_lshl_b64 s[4:5], s[4:5], 14
	v_cvt_pk_bf16_f32 v58, v18, v19
	v_cvt_pk_bf16_f32 v59, v20, v21
	v_mfma_f32_16x16x32_bf16 v[14:17], v[62:65], v[14:17], 0
	v_cvt_pk_bf16_f32 v60, v22, v23
	v_cvt_pk_bf16_f32 v61, v24, v25
	v_cvt_pk_bf16_f32 v54, v34, v35
	s_waitcnt vmcnt(18)
	v_mfma_f32_16x16x32_bf16 v[114:117], v[66:69], v[10:13], v[50:53]
	ds_read_b128 v[66:69], v181 offset:0x1280
	s_waitcnt lgkmcnt(10)
	v_cvt_pk_bf16_f32 v55, v36, v37
	v_mfma_f32_16x16x32_bf16 v[106:109], v[106:109], v[10:13], v[14:17]
	v_or_b32_e32 v11, s5, v175
	v_or_b32_e32 v10, s4, v174
	v_lshl_add_u64 v[10:11], v[172:173], 0, v[10:11]
	global_load_dwordx4 v[14:17], v[10:11], off
	s_nop 0
	global_load_dwordx4 v[10:13], v[10:11], off offset:64
	ds_read_b128 v[126:129], v181 offset:0x2480
	s_waitcnt lgkmcnt(10)
	v_cvt_pk_bf16_f32 v50, v26, v27
	v_mfma_f32_16x16x32_bf16 v[102:105], v[102:105], v[58:61], v[118:121]
	ds_read_b128 v[118:121], v181 offset:0x3680
	s_waitcnt lgkmcnt(10)
	v_cvt_pk_bf16_f32 v51, v28, v29
	v_mfma_f32_16x16x32_bf16 v[98:101], v[98:101], v[58:61], v[110:113]
	ds_read_b128 v[110:113], v181 offset:0xc0
	s_waitcnt lgkmcnt(10)
	ds_read_b128 v[134:137], v181 offset:0x12c0
	s_waitcnt lgkmcnt(10)
	v_cvt_pk_bf16_f32 v52, v30, v31
	v_mfma_f32_16x16x32_bf16 v[94:97], v[94:97], v[58:61], v[114:117]
	v_cvt_pk_bf16_f32 v53, v32, v33
	v_cvt_pk_bf16_f32 v56, v38, v39
	v_cvt_pk_bf16_f32 v57, v40, v41
	v_mfma_f32_16x16x32_bf16 v[90:93], v[90:93], v[58:61], v[106:109]
	ds_read_b128 v[106:109], v181 offset:0x24c0
	s_waitcnt lgkmcnt(10)
	v_cvt_pk_bf16_f32 v62, v42, v43
	v_mfma_f32_16x16x32_bf16 v[86:89], v[86:89], v[50:53], v[102:105]
	ds_read_b128 v[102:105], v181 offset:0x36c0
	s_waitcnt lgkmcnt(10)
	ds_read_b128 v[158:161], v181 offset:0x4800
	s_waitcnt lgkmcnt(10)
	ds_read_b128 v[154:157], v181 offset:0x5a00
	s_waitcnt lgkmcnt(10)
	v_cvt_pk_bf16_f32 v63, v44, v45
	v_mfma_f32_16x16x32_bf16 v[82:85], v[82:85], v[50:53], v[98:101]
	v_cvt_pk_bf16_f32 v64, v46, v47
	v_cvt_pk_bf16_f32 v65, v48, v49
	s_and_b32 s5, s11, 0xffff
	v_mfma_f32_16x16x32_bf16 v[78:81], v[78:81], v[50:53], v[94:97]
	ds_read_b128 v[94:97], v181 offset:0x4840
	s_waitcnt lgkmcnt(10)
	ds_read_b128 v[114:117], v181 offset:0x5a40
	s_waitcnt lgkmcnt(10)
	v_mfma_f32_16x16x32_bf16 v[74:77], v[74:77], v[50:53], v[90:93]
	ds_read_b128 v[122:125], v181 offset:0x4880
	s_waitcnt lgkmcnt(10)
	ds_read_b128 v[130:133], v181 offset:0x5a80
	v_mfma_f32_16x16x32_bf16 v[70:73], v[70:73], v[54:57], v[86:89]
	s_waitcnt lgkmcnt(10)
	ds_read_b128 v[138:141], v181 offset:0x48c0
	s_waitcnt lgkmcnt(10)
	v_mfma_f32_16x16x32_bf16 v[66:69], v[66:69], v[54:57], v[82:85]
	ds_read_b128 v[142:145], v181 offset:0x5ac0
	s_waitcnt lgkmcnt(10)
	ds_read_b128 v[162:165], v183 offset:0x200
	v_mfma_f32_16x16x32_bf16 v[78:81], v[126:129], v[54:57], v[78:81]
	s_waitcnt lgkmcnt(10)
	ds_read_b128 v[166:169], v183 offset:0x240
	s_waitcnt lgkmcnt(10)
	v_mfma_f32_16x16x32_bf16 v[74:77], v[118:121], v[54:57], v[74:77]
	ds_read_b128 v[186:189], v183 offset:0x280
	s_waitcnt lgkmcnt(10)
	ds_read_b128 v[190:193], v183 offset:0x2c0
	v_mfma_f32_16x16x32_bf16 v[146:149], v[110:113], v[62:65], v[70:73]
	s_waitcnt lgkmcnt(10)
	ds_read_b32 v194, v185 offset:0x1fc
	s_waitcnt lgkmcnt(10)
	v_mfma_f32_16x16x32_bf16 v[150:153], v[134:137], v[62:65], v[66:69]
	ds_read_b128 v[134:137], v182 offset:0
	s_waitcnt lgkmcnt(10)
	ds_read_b128 v[126:129], v182 offset:0xa00
	v_mfma_f32_16x16x32_bf16 v[106:109], v[106:109], v[62:65], v[78:81]
	s_waitcnt lgkmcnt(10)
	ds_read_b128 v[118:121], v182 offset:0x1400
	s_waitcnt lgkmcnt(10)
	v_mfma_f32_16x16x32_bf16 v[74:77], v[102:105], v[62:65], v[74:77]
	ds_read_b128 v[110:113], v182 offset:0x1e00
	s_waitcnt lgkmcnt(10)
	ds_read_b128 v[98:101], v182 offset:0x2800
	s_waitcnt lgkmcnt(10)
	s_nop 4
	v_cvt_pk_bf16_f32 v70, v146, v147
	v_cvt_pk_bf16_f32 v71, v148, v149
	v_cvt_pk_bf16_f32 v72, v150, v151
	v_cvt_pk_bf16_f32 v73, v152, v153
	ds_read_b128 v[102:105], v182 offset:0x3200
	s_waitcnt lgkmcnt(10)
	ds_read_b128 v[90:93], v182 offset:0x3c00
	s_waitcnt lgkmcnt(10)
	v_cvt_pk_bf16_f32 v66, v106, v107
	v_pk_mul_f32 v[148:149], v[148:149], v[164:165]
	v_pk_mul_f32 v[146:147], v[146:147], v[162:163]
	v_pk_mul_f32 v[152:153], v[152:153], v[168:169]
	v_pk_mul_f32 v[150:151], v[150:151], v[166:167]
	v_cvt_pk_bf16_f32 v67, v108, v109
	ds_read_b128 v[86:89], v182 offset:0x4600
	s_waitcnt lgkmcnt(10)
	ds_read_b128 v[82:85], v182 offset:64
	s_waitcnt lgkmcnt(10)
	ds_read_b128 v[78:81], v182 offset:0xa40
	s_waitcnt lgkmcnt(10)
	v_cvt_pk_bf16_f32 v69, v76, v77
	v_pk_mul_f32 v[162:163], v[108:109], v[188:189]
	v_pk_mul_f32 v[164:165], v[106:107], v[186:187]
	v_cvt_pk_bf16_f32 v106, v146, v147
	v_cvt_pk_bf16_f32 v107, v148, v149
	v_cvt_pk_bf16_f32 v108, v150, v151
	v_cvt_pk_bf16_f32 v109, v152, v153
	v_pk_mul_f32 v[152:153], v[194:195], v[28:29] op_sel_hi:[0,1]
	v_pk_mul_f32 v[150:151], v[194:195], v[26:27] op_sel_hi:[0,1]
	v_pk_mul_f32 v[148:149], v[194:195], v[32:33] op_sel_hi:[0,1]
	v_pk_mul_f32 v[146:147], v[194:195], v[30:31] op_sel_hi:[0,1]
	v_pk_mul_f32 v[32:33], v[194:195], v[36:37] op_sel_hi:[0,1]
	v_pk_mul_f32 v[30:31], v[194:195], v[34:35] op_sel_hi:[0,1]
	v_pk_mul_f32 v[28:29], v[194:195], v[40:41] op_sel_hi:[0,1]
	v_pk_mul_f32 v[26:27], v[194:195], v[38:39] op_sel_hi:[0,1]
	v_mfma_f32_16x16x32_bf16 v[34:37], v[158:161], v[58:61], 0
	v_mul_f32_e64 v166, v76, v192
	v_mul_f32_e64 v167, v77, v193
	v_pk_mul_f32 v[76:77], v[74:75], v[190:191]
	v_pk_mul_f32 v[168:169], v[194:195], v[20:21] op_sel_hi:[0,1]
	v_mfma_f32_16x16x32_bf16 v[38:41], v[154:157], v[58:61], 0
	v_cvt_pk_bf16_f32 v76, v76, v77
	v_cvt_pk_bf16_f32 v77, v166, v167
	v_pk_mul_f32 v[166:167], v[194:195], v[18:19] op_sel_hi:[0,1]
	v_mfma_f32_16x16x32_bf16 v[34:37], v[94:97], v[50:53], v[34:37]
	v_cvt_pk_bf16_f32 v68, v74, v75
	v_cvt_pk_bf16_f32 v74, v164, v165
	v_cvt_pk_bf16_f32 v75, v162, v163
	v_mfma_f32_16x16x32_bf16 v[38:41], v[114:117], v[50:53], v[38:41]
	v_mul_f32_e64 v164, v194, v24
	v_mul_f32_e64 v165, v194, v25
	v_pk_mul_f32 v[162:163], v[194:195], v[22:23] op_sel_hi:[0,1]
	v_pk_mul_f32 v[24:25], v[194:195], v[44:45] op_sel_hi:[0,1]
	v_mfma_f32_16x16x32_bf16 v[34:37], v[122:125], v[54:57], v[34:37]
	v_mul_f32_e64 v22, v194, v42
	v_mul_f32_e64 v23, v194, v43
	v_pk_mul_f32 v[20:21], v[194:195], v[48:49] op_sel_hi:[0,1]
	v_pk_mul_f32 v[18:19], v[194:195], v[46:47] op_sel_hi:[0,1]
	v_mfma_f32_16x16x32_bf16 v[38:41], v[130:133], v[54:57], v[38:41]
	s_mov_b32 s4, s10
	s_add_u32 s10, s10, 0x40000
	s_addc_u32 s11, s11, 0
	v_mfma_f32_16x16x32_bf16 v[114:117], v[138:141], v[62:65], v[34:37]
	ds_read_b128 v[34:37], v182 offset:0x1440
	s_waitcnt lgkmcnt(10)
	ds_read_b128 v[42:45], v182 offset:0x1e40
	v_mfma_f32_16x16x32_bf16 v[94:97], v[142:145], v[62:65], v[38:41]
	s_waitcnt lgkmcnt(10)
	ds_read_b128 v[122:125], v182 offset:0x2840
	s_waitcnt lgkmcnt(10)
	v_mfma_f32_16x16x32_bf16 v[38:41], v[134:137], v[106:109], v[166:169]
	s_cmp_gt_u32 s22, 61
	v_mfma_f32_16x16x32_bf16 v[46:49], v[126:129], v[106:109], v[162:165]
	ds_read_b128 v[126:129], v182 offset:0x3240
	s_waitcnt lgkmcnt(10)
	ds_read_b128 v[130:133], v182 offset:0x3c40
	s_waitcnt lgkmcnt(10)
	ds_read_b128 v[134:137], v182 offset:0x4640
	s_waitcnt lgkmcnt(10)
	v_mfma_f32_16x16x32_bf16 v[118:121], v[118:121], v[106:109], v[150:153]
	ds_read_b128 v[138:141], v182 offset:0x7800
	s_waitcnt lgkmcnt(10)
	ds_read_b128 v[142:145], v182 offset:0x8200
	v_mfma_f32_16x16x32_bf16 v[110:113], v[110:113], v[106:109], v[146:149]
	s_waitcnt lgkmcnt(10)
	v_mfma_f32_16x16x32_bf16 v[98:101], v[98:101], v[106:109], v[30:33]
	v_mfma_f32_16x16x32_bf16 v[102:105], v[102:105], v[106:109], v[26:29]
	v_mfma_f32_16x16x32_bf16 v[90:93], v[90:93], v[106:109], v[22:25]
	v_mfma_f32_16x16x32_bf16 v[18:21], v[86:89], v[106:109], v[18:21]
	ds_read_b128 v[86:89], v182 offset:0x8c00
	s_waitcnt lgkmcnt(10)
	s_nop 0
	v_mfma_f32_16x16x32_bf16 v[22:25], v[82:85], v[74:77], v[38:41]
	ds_read_b128 v[82:85], v182 offset:0x9600
	s_waitcnt lgkmcnt(10)
	s_nop 0
	v_mfma_f32_16x16x32_bf16 v[26:29], v[78:81], v[74:77], v[46:49]
	ds_read_b128 v[78:81], v182 offset:0x8c40
	s_waitcnt lgkmcnt(10)
	ds_read_b128 v[106:109], v182 offset:0x9640
	s_waitcnt lgkmcnt(10)
	s_nop 0
	v_mfma_f32_16x16x32_bf16 v[30:33], v[34:37], v[74:77], v[118:121]
	v_mfma_f32_16x16x32_bf16 v[34:37], v[42:45], v[74:77], v[110:113]
	ds_read_b128 v[110:113], v181 offset:0x6c00
	s_waitcnt lgkmcnt(10)
	s_nop 0
	v_mfma_f32_16x16x32_bf16 v[38:41], v[122:125], v[74:77], v[98:101]
	ds_read_b128 v[98:101], v181 offset:0x7e00
	s_waitcnt lgkmcnt(10)
	s_nop 0
	v_mfma_f32_16x16x32_bf16 v[42:45], v[126:129], v[74:77], v[102:105]
	ds_read_b128 v[102:105], v181 offset:0x6c40
	s_waitcnt lgkmcnt(10)
	s_nop 0
	v_mfma_f32_16x16x32_bf16 v[46:49], v[130:133], v[74:77], v[90:93]
	ds_read_b128 v[90:93], v181 offset:0x7e40
	s_waitcnt lgkmcnt(10)
	s_nop 0
	v_mfma_f32_16x16x32_bf16 v[18:21], v[134:137], v[74:77], v[18:21]
	ds_read_b128 v[74:77], v181 offset:0x6c80
	s_waitcnt lgkmcnt(10)
	ds_read_b128 v[122:125], v181 offset:0x7e80
	s_waitcnt lgkmcnt(10)
	ds_read_b128 v[130:133], v181 offset:0x6cc0
	s_waitcnt lgkmcnt(10)
	ds_read_b128 v[134:137], v181 offset:0x7ec0
	s_nop 0
	v_mfma_f32_16x16x32_bf16 v[118:121], v[138:141], v[70:73], 0
	s_waitcnt lgkmcnt(10)
	v_mfma_f32_16x16x32_bf16 v[86:89], v[86:89], v[70:73], 0
	v_mfma_f32_16x16x32_bf16 v[126:129], v[142:145], v[70:73], 0
	v_mfma_f32_16x16x32_bf16 v[70:73], v[82:85], v[70:73], 0
	ds_read_b128 v[82:85], v183 offset:0x100
	s_waitcnt lgkmcnt(10)
	s_nop 0
	v_mfma_f32_16x16x32_bf16 v[78:81], v[78:81], v[66:69], v[86:89]
	ds_read_b128 v[86:89], v183 offset:0x140
	s_waitcnt lgkmcnt(10)
	s_nop 0
	v_mfma_f32_16x16x32_bf16 v[66:69], v[106:109], v[66:69], v[70:73]
	ds_read_b128 v[70:73], v183 offset:0x180
	s_waitcnt lgkmcnt(10)
	s_nop 0
	v_mfma_f32_16x16x32_bf16 v[106:109], v[110:113], v[58:61], 0
	ds_read_b128 v[110:113], v183 offset:0x1c0
	s_waitcnt lgkmcnt(10)
	s_waitcnt lgkmcnt(9)
	s_waitcnt lgkmcnt(8)
	s_waitcnt lgkmcnt(7)
	s_waitcnt lgkmcnt(6)
	s_waitcnt lgkmcnt(5)
	s_nop 0
	v_mfma_f32_16x16x32_bf16 v[58:61], v[98:101], v[58:61], 0
	s_waitcnt lgkmcnt(4)
	s_waitcnt lgkmcnt(3)
	s_waitcnt lgkmcnt(2)
	v_mfma_f32_16x16x32_bf16 v[98:101], v[102:105], v[50:53], v[106:109]
	s_waitcnt lgkmcnt(1)
	s_waitcnt lgkmcnt(0)
	v_mfma_f32_16x16x32_bf16 v[50:53], v[90:93], v[50:53], v[58:61]
	v_mfma_f32_16x16x32_bf16 v[58:61], v[74:77], v[54:57], v[98:101]
	v_mfma_f32_16x16x32_bf16 v[50:53], v[122:125], v[54:57], v[50:53]
	v_mfma_f32_16x16x32_bf16 v[54:57], v[130:133], v[62:65], v[58:61]
	s_nop 5
	v_fma_f32 v58, v116, v84, v120
	v_fma_f32 v59, v117, v85, v121
	v_pk_fma_f32 v[60:61], v[114:115], v[82:83], v[118:119]
	v_cvt_pk_bf16_f32 v58, v58, v59
	v_cvt_pk_bf16_f32 v60, v60, v61
	v_mfma_f32_16x16x32_bf16 v[50:53], v[134:137], v[62:65], v[50:53]
	v_mov_b32_dpp v59, v58 quad_perm:[1,0,3,2] row_mask:0xf bank_mask:0xf bound_ctrl:1
	v_mov_b32_dpp v61, v60 quad_perm:[1,0,3,2] row_mask:0xf bank_mask:0xf bound_ctrl:1
	v_pk_fma_f32 v[64:65], v[94:95], v[86:87], v[126:127]
	v_perm_b32 v60, v61, v60, v176
	v_perm_b32 v58, v59, v58, v176
	buffer_store_dword v60, v177, s[4:7], 0 offen
	buffer_store_dword v58, v177, s[4:7], s14 offen
	v_cvt_pk_bf16_f32 v58, v64, v65
	v_pk_fma_f32 v[62:63], v[96:97], v[88:89], v[128:129]
	v_pk_fma_f32 v[54:55], v[54:55], v[70:71], v[78:79]
	v_mov_b32_dpp v59, v58 quad_perm:[1,0,3,2] row_mask:0xf bank_mask:0xf bound_ctrl:1
	v_perm_b32 v58, v59, v58, v176
	buffer_store_dword v58, v177, s[4:7], s15 offen
	v_cvt_pk_bf16_f32 v58, v62, v63
	v_cvt_pk_bf16_f32 v54, v54, v55
	v_pk_fma_f32 v[56:57], v[56:57], v[72:73], v[80:81]
	v_mov_b32_dpp v59, v58 quad_perm:[1,0,3,2] row_mask:0xf bank_mask:0xf bound_ctrl:1
	v_mov_b32_dpp v55, v54 quad_perm:[1,0,3,2] row_mask:0xf bank_mask:0xf bound_ctrl:1
	v_pk_fma_f32 v[50:51], v[50:51], v[110:111], v[66:67]
	v_perm_b32 v58, v59, v58, v176
	v_perm_b32 v54, v55, v54, v176
	buffer_store_dword v58, v177, s[4:7], s3 offen
	buffer_store_dword v54, v177, s[4:7], s18 offen
	v_cvt_pk_bf16_f32 v54, v56, v57
	v_cvt_pk_bf16_f32 v50, v50, v51
	v_pk_fma_f32 v[52:53], v[52:53], v[112:113], v[68:69]
	v_mov_b32_dpp v55, v54 quad_perm:[1,0,3,2] row_mask:0xf bank_mask:0xf bound_ctrl:1
	v_mov_b32_dpp v51, v50 quad_perm:[1,0,3,2] row_mask:0xf bank_mask:0xf bound_ctrl:1
	v_perm_b32 v54, v55, v54, v176
	v_perm_b32 v50, v51, v50, v176
	buffer_store_dword v54, v177, s[4:7], s19 offen
	buffer_store_dword v50, v177, s[4:7], s20 offen
	v_cvt_pk_bf16_f32 v50, v52, v53
	s_nop 1
	v_mov_b32_dpp v51, v50 quad_perm:[1,0,3,2] row_mask:0xf bank_mask:0xf bound_ctrl:1
	v_perm_b32 v50, v51, v50, v176
	buffer_store_dword v50, v177, s[4:7], s21 offen
	s_waitcnt lgkmcnt(0)
	s_barrier
	s_cbranch_scc0 .LBB0_351
	s_setprio 0
	s_mov_b64 s[2:3], 0

.LBB0_364:
	s_waitcnt vmcnt(0)
	ds_write_b128 v143, v[6:9]
	s_waitcnt vmcnt(29)
	ds_write_b128 v143, v[14:17] offset:18432
	s_waitcnt vmcnt(27)
	ds_write_b128 v144, v[22:25] offset:36864
	ds_write_b128 v143, v[2:5] offset:4608
	ds_write_b128 v143, v[10:13] offset:23040
	s_waitcnt vmcnt(26)
	ds_write_b128 v144, v[18:21] offset:41984
	s_waitcnt vmcnt(25)
	ds_write_b128 v143, v[30:33] offset:9216
	s_waitcnt vmcnt(23)
	ds_write_b128 v143, v[38:41] offset:27648
	s_waitcnt vmcnt(21)
	ds_write_b128 v144, v[42:45] offset:47104
	ds_write_b128 v143, v[26:29] offset:13824
	ds_write_b128 v143, v[34:37] offset:32256
	s_waitcnt vmcnt(20)
	ds_write_b128 v144, v[46:49] offset:52224
	s_waitcnt vmcnt(19)
	ds_write_b128 v144, v[50:53] offset:57344
	s_waitcnt vmcnt(17)
	ds_write_b128 v145, v[58:61]
	ds_write_b128 v144, v[54:57] offset:62464
	s_waitcnt vmcnt(16)
	ds_write_b128 v145, v[62:65] offset:5120
	s_and_saveexec_b64 s[12:13], vcc
	s_cbranch_execz .LBB0_366
	v_mul_f32_e32 v2, 0x3fb8aa3b, v135
	v_sub_f32_e32 v3, v136, v135
	v_exp_f32_e32 v2, v2
	v_mul_f32_e32 v3, 0x3fb8aa3b, v3
	v_exp_f32_e32 v3, v3
	ds_write_b32 v139, v2
	ds_write_b32 v140, v3

.LBB0_370:
	s_or_b64 exec, exec, s[12:13]
	s_waitcnt lgkmcnt(0)
	s_barrier
	v_add_u32_e32 v147, 0x13000, v143
	s_waitcnt vmcnt(0)
	ds_write_b128 v147, v[70:73]
	v_add_u32_e32 v70, 0x17800, v143
	v_add_u32_e32 v71, 0x1c000, v144
	s_waitcnt vmcnt(29)
	ds_write_b128 v70, v[78:81]
	s_waitcnt vmcnt(27)
	ds_write_b128 v71, v[86:89]
	ds_write_b128 v147, v[66:69] offset:4608
	ds_write_b128 v70, v[74:77] offset:4608
	s_waitcnt vmcnt(26)
	ds_write_b128 v71, v[82:85] offset:5120
	s_waitcnt vmcnt(25)
	ds_write_b128 v147, v[94:97] offset:9216
	s_waitcnt vmcnt(23)
	ds_write_b128 v70, v[102:105] offset:9216
	s_waitcnt vmcnt(21)
	ds_write_b128 v71, v[106:109] offset:10240
	ds_write_b128 v147, v[90:93] offset:13824
	ds_write_b128 v70, v[98:101] offset:13824
	s_waitcnt vmcnt(20)
	ds_write_b128 v71, v[110:113] offset:15360
	v_add_u32_e32 v66, 0x21000, v144
	v_add_u32_e32 v67, 0x23800, v144
	s_waitcnt vmcnt(19)
	ds_write_b128 v66, v[118:121]
	s_waitcnt vmcnt(17)
	ds_write_b128 v67, v[122:125]
	ds_write_b128 v66, v[114:117] offset:5120
	s_waitcnt vmcnt(16)
	ds_write_b128 v67, v[126:129] offset:5120
	s_and_saveexec_b64 s[12:13], vcc
	s_cbranch_execz .LBB0_372
	v_mul_f32_e32 v66, 0x3fb8aa3b, v137
	v_sub_f32_e32 v67, v138, v137
	v_exp_f32_e32 v66, v66
	v_mul_f32_e32 v67, 0x3fb8aa3b, v67
	v_exp_f32_e32 v67, v67
	ds_write_b32 v141, v66
	ds_write_b32 v142, v67
